# final combine+LN phase: row-level load ladder (all row loads in flight at once, split-K tail ids fetched as two 16-byte loads; rows with a split block fall back to the step-by-step ladder)
# baseline (speedup 1.0000x reference)
; template <int SRC, int EXTRA, bool OUT8 = false> ...
;     ...
;             const int p0 = pos[2 * row], p1 = pos[2 * row + 1]; const float w0 = gwt[2 * row], w1 = gwt[2 * row + 1]; const float hm = hp.stats[2 * row], hr = hp.stats[2 * row + 1];
; #pragma unroll
;             for (int j = 0; j < 4; ++j) { const f32x4 a = (*(const f32x4*)(hp.src + (size_t)row * 1024 + 256 * j + 4 * lane) - hm) * hr * *(const f32x4*)(hp.g + 256 * j + 4 * lane) + *(const f32x4*)(hp.b + 256 * j + 4 * lane);
;                 f32x4 y[2];
; #pragma unroll
;                 for (int q = 0; q < 2; ++q) { const int p = q ? p1 : p0; const int t = __builtin_amdgcn_readfirstlane(tailid[(p >> 8) * 4 + j]);
;                     if (t < 0) y[q] = *(const f32x4*)(ys + (size_t)p * 1024 + 256 * j + 4 * lane);
;                     else { f32x4 acc = (f32x4){0.f, 0.f, 0.f, 0.f};
; #pragma unroll
;                         for (int sl = 0; sl < 7; ++sl) acc = acc + *(const f32x4*)(part + ((size_t)(t * 7 + sl) * 256 + (p & 255)) * 256 + 4 * lane);
;                         y[q] = acc; } }
;                 v[j] = a * ALPHA + y[0] * w0 + y[1] * w1; }
.LBB0_2246:
	s_ashr_i32 s7, s6, 31
	s_lshl_b64 s[0:1], s[6:7], 2
	s_add_u32 s16, s26, s0
	s_addc_u32 s17, s27, s1
	global_load_dwordx2 v[44:45], v113, s[16:17]
	s_add_u32 s20, s28, s0
	s_addc_u32 s21, s29, s1
	s_add_u32 s0, s24, s0
	s_addc_u32 s1, s25, s1
	global_load_dwordx2 v[124:125], v113, s[0:1]
	global_load_dwordx2 v[122:123], v113, s[20:21]
	v_lshl_add_u64 v[160:161], s[8:9], 0, v[112:113]
	v_add_co_u32_e32 v160, vcc, s31, v160
	s_nop 1
	v_addc_co_u32_e32 v161, vcc, 0, v161, vcc
	global_load_dwordx4 v[40:43], v[160:161], off
	global_load_dwordx4 v[60:63], v[160:161], off offset:1024
	global_load_dwordx4 v[80:83], v[160:161], off offset:2048
	global_load_dwordx4 v[100:103], v[160:161], off offset:3072
	global_load_dwordx4 v[32:35], v[114:115], off
	global_load_dwordx4 v[52:55], v[114:115], off offset:1024
	global_load_dwordx4 v[72:75], v[114:115], off offset:2048
	global_load_dwordx4 v[88:91], v[114:115], off offset:3072
	global_load_dwordx4 v[36:39], v[116:117], off
	global_load_dwordx4 v[56:59], v[116:117], off offset:1024
	global_load_dwordx4 v[76:79], v[116:117], off offset:2048
	global_load_dwordx4 v[92:95], v[116:117], off offset:3072
	s_waitcnt vmcnt(14)
	v_readfirstlane_b32 s16, v44
	v_readfirstlane_b32 s22, v45
	s_ashr_i32 s0, s16, 6
	s_and_b32 s0, s0, -4
	s_ashr_i32 s1, s0, 31
	s_lshl_b64 s[0:1], s[0:1], 2
	s_add_u32 s18, s36, s0
	s_addc_u32 s19, s37, s1
	s_ashr_i32 s0, s22, 6
	s_and_b32 s0, s0, -4
	s_ashr_i32 s1, s0, 31
	s_lshl_b64 s[0:1], s[0:1], 2
	s_add_u32 s20, s36, s0
	s_addc_u32 s21, s37, s1
	global_load_dwordx4 v[168:171], v113, s[18:19]
	global_load_dwordx4 v[172:175], v113, s[20:21]
	s_ashr_i32 s17, s16, 31
	s_lshl_b64 s[0:1], s[16:17], 12
	v_lshl_add_u64 v[162:163], v[120:121], 0, s[0:1]
	s_ashr_i32 s23, s22, 31
	s_lshl_b64 s[0:1], s[22:23], 12
	v_lshl_add_u64 v[164:165], v[120:121], 0, s[0:1]
	global_load_dwordx4 v[44:47], v[162:163], off
	global_load_dwordx4 v[64:67], v[162:163], off offset:1024
	global_load_dwordx4 v[84:87], v[162:163], off offset:2048
	global_load_dwordx4 v[104:107], v[162:163], off offset:3072
	global_load_dwordx4 v[48:51], v[164:165], off
	global_load_dwordx4 v[68:71], v[164:165], off offset:1024
	global_load_dwordx4 v[96:99], v[164:165], off offset:2048
	global_load_dwordx4 v[108:111], v[164:165], off offset:3072
	s_waitcnt vmcnt(8)
	v_and_b32_e32 v168, v168, v169
	v_and_b32_e32 v170, v170, v171
	v_and_b32_e32 v172, v172, v173
	v_and_b32_e32 v174, v174, v175
	v_and_b32_e32 v168, v168, v170
	v_and_b32_e32 v172, v172, v174
	v_and_b32_e32 v168, v168, v172
	s_nop 0
	v_readfirstlane_b32 s0, v168
	s_waitcnt vmcnt(0)
	s_cmp_lt_i32 s0, 0
	s_cbranch_scc0 .Lcomb_slow
	s_branch .LBB0_2278
